# stackG + static s_setprio 1 for waves 4-7 around the ADIFF fast loop
# speedup vs baseline: 1.0030x; 1.0030x over previous
; #define LAS __attribute__((address_space(3)))
; __device__ __forceinline__ void diff_attn_phase(const Params& p, LAS unsigned char* lds) {
;     ...
;         for (int ch = 0; ch < NCH; ++ch) {
;             if (ch + 1 < NCH) asm volatile("s_waitcnt vmcnt(4)" ::: "memory"); else asm volatile("s_waitcnt vmcnt(0)" ::: "memory");
;             __builtin_amdgcn_s_barrier(); asm volatile("" ::: "memory");
;             if (ch + 2 < NCH) issue(ch + 2, s_nn);
;             const LAS unsigned char* Ksb = lds + s_cur * STG; const LAS unsigned char* Vsb = Ksb + 16384;
;             s_nn = s_cur; s_cur = (s_cur == 2) ? 0 : s_cur + 1;
; #pragma clang loop unroll(disable)
;             for (int u = 0; u < 2; ++u) {
;                 const LAS unsigned char* Ku = Ksb + u * 8192; const LAS unsigned char* Vu = Vsb + u * 8192;
;                 int kxl = kx, vb0l = vb0, vb1l = vb1; asm volatile("" : "+v"(kxl), "+v"(vb0l), "+v"(vb1l));
;                 bf16x8 kf[4];
; #pragma unroll
;                 for (int ks = 0; ks < 4; ++ks) kf[ks] = *(const LAS bf16x8*)(Ku + kbase + (kxl ^ (32 * ks)));
;                 bf16x8 P[2][2];
; #pragma unroll
;                 for (int r = 0; r < 2; ++r) {
;                     f32x16 S;
; #pragma unroll
;                     for (int i = 0; i < 16; ++i) S[i] = 0.f;
; #pragma unroll
;                     for (int ks = 0; ks < 4; ++ks) S = __builtin_amdgcn_mfma_f32_32x32x16_bf16(kf[ks], qf[r][ks], S, 0, 0, 0);
;                     S = __builtin_amdgcn_mfma_f32_32x32x16_bf16(kone, qm[r], S, 0, 0, 0);
; #pragma unroll
;                     for (int i = 0; i < 16; ++i) S[i] = __builtin_amdgcn_exp2f(S[i]);
;                     l[r] += sum16(S);
;                     P[r][0] = pack8(S, 0); P[r][1] = pack8(S, 8);
;                 }
; #pragma unroll
;                 for (int t = 0; t < 4; ++t) {
;                     const LAS unsigned char* a0 = Vu + (vb0l ^ (64 * t)); const LAS unsigned char* a1 = Vu + (vb1l ^ (64 * t));
;                     const bf16x8 v0 = tr_pair(a0, a1), v1 = tr_pair(a0 + 4096, a1 + 4096);
;                     O[0][t] = __builtin_amdgcn_mfma_f32_32x32x16_bf16(v0, P[0][0], O[0][t], 0, 0, 0);
;                     O[1][t] = __builtin_amdgcn_mfma_f32_32x32x16_bf16(v0, P[1][0], O[1][t], 0, 0, 0);
;                     O[0][t] = __builtin_amdgcn_mfma_f32_32x32x16_bf16(v1, P[0][1], O[0][t], 0, 0, 0);
.Lfa_entry:
	s_cmp_lg_u32 s44, 0
	s_cbranch_scc0 .Lfa_noprio
	s_setprio 1

; #define LAS __attribute__((address_space(3)))
; __device__ __forceinline__ void diff_attn_phase(const Params& p, LAS unsigned char* lds) {
;     ...
; #pragma unroll
;                     for (int i = 0; i < 16; ++i) S[i] = __builtin_amdgcn_exp2f(S[i]);
;                     l[r] += sum16(S);
;                     P[r][0] = pack8(S, 0); P[r][1] = pack8(S, 8);
;                 }
; #pragma unroll
;                 for (int t = 0; t < 4; ++t) {
;                     const LAS unsigned char* a0 = Vu + (vb0l ^ (64 * t)); const LAS unsigned char* a1 = Vu + (vb1l ^ (64 * t));
;                     const bf16x8 v0 = tr_pair(a0, a1), v1 = tr_pair(a0 + 4096, a1 + 4096);
;                     O[0][t] = __builtin_amdgcn_mfma_f32_32x32x16_bf16(v0, P[0][0], O[0][t], 0, 0, 0);
;                     O[1][t] = __builtin_amdgcn_mfma_f32_32x32x16_bf16(v0, P[1][0], O[1][t], 0, 0, 0);
;                     O[0][t] = __builtin_amdgcn_mfma_f32_32x32x16_bf16(v1, P[0][1], O[0][t], 0, 0, 0);
;                     O[1][t] = __builtin_amdgcn_mfma_f32_32x32x16_bf16(v1, P[1][1], O[1][t], 0, 0, 0);
;                 }
.Lfb_last0F:
	s_waitcnt lgkmcnt(6)
	v_mfma_f32_32x32x16_bf16 v[114:129], v[198:201], v[222:225], v[114:129]
	v_add_f32_e32 v213, v213, v153
	v_add_f32_e32 v212, v212, v137
	v_cvt_pk_bf16_f32 v214, v146, v147
	v_cvt_pk_bf16_f32 v218, v130, v131
	v_cvt_pk_bf16_f32 v215, v148, v149
	v_cvt_pk_bf16_f32 v219, v132, v133
	v_cvt_pk_bf16_f32 v216, v150, v151
	v_cvt_pk_bf16_f32 v220, v134, v135
	v_cvt_pk_bf16_f32 v217, v152, v153
	v_cvt_pk_bf16_f32 v221, v136, v137
	v_mfma_f32_32x32x16_bf16 v[50:65], v[198:201], v[226:229], v[50:65]
	ds_read_b64_tr_b16 v[198:199], v234 offset:24576
	ds_read_b64_tr_b16 v[200:201], v235 offset:24576
	v_exp_f32_e32 v154, v154
	v_exp_f32_e32 v138, v138
	v_exp_f32_e32 v155, v155
	v_exp_f32_e32 v139, v139
	v_add_f32_e32 v213, v213, v154
	s_waitcnt lgkmcnt(6)
	v_mfma_f32_32x32x16_bf16 v[98:113], v[202:205], v[222:225], v[98:113]
	v_add_f32_e32 v212, v212, v138
	v_add_f32_e32 v213, v213, v155
	v_add_f32_e32 v212, v212, v139
	v_exp_f32_e32 v156, v156
	v_exp_f32_e32 v140, v140
	v_mfma_f32_32x32x16_bf16 v[34:49], v[202:205], v[226:229], v[34:49]
	ds_read_b64_tr_b16 v[202:203], v237 offset:24576
	ds_read_b64_tr_b16 v[204:205], v236 offset:24576
	v_exp_f32_e32 v157, v157
	v_exp_f32_e32 v141, v141
	v_add_f32_e32 v213, v213, v156
	v_add_f32_e32 v212, v212, v140
	v_add_f32_e32 v213, v213, v157
	s_waitcnt lgkmcnt(6)
	v_mfma_f32_32x32x16_bf16 v[82:97], v[208:211], v[222:225], v[82:97]
	v_add_f32_e32 v212, v212, v141
	v_exp_f32_e32 v158, v158
	v_exp_f32_e32 v142, v142
	v_exp_f32_e32 v159, v159
	v_exp_f32_e32 v143, v143
	v_mfma_f32_32x32x16_bf16 v[18:33], v[208:211], v[226:229], v[18:33]
	ds_read_b64_tr_b16 v[208:209], v238 offset:24576
	ds_read_b64_tr_b16 v[210:211], v239 offset:24576
	v_add_f32_e32 v213, v213, v158
	v_add_f32_e32 v212, v212, v142
	v_add_f32_e32 v213, v213, v159
	v_add_f32_e32 v212, v212, v143
	s_waitcnt lgkmcnt(6)
	v_mfma_f32_32x32x16_bf16 v[66:81], v[230:233], v[222:225], v[66:81]
	v_exp_f32_e32 v160, v160
	v_exp_f32_e32 v144, v144
	v_exp_f32_e32 v161, v161
	v_exp_f32_e32 v145, v145
	v_mfma_f32_32x32x16_bf16 v[2:17], v[230:233], v[226:229], v[2:17]
	ds_read_b64_tr_b16 v[230:231], v250 offset:24576
	ds_read_b64_tr_b16 v[232:233], v251 offset:24576
	v_add_f32_e32 v213, v213, v160
	v_add_f32_e32 v212, v212, v144
	v_add_f32_e32 v213, v213, v161
	v_add_f32_e32 v212, v212, v145
	v_cvt_pk_bf16_f32 v222, v154, v155
	v_cvt_pk_bf16_f32 v226, v138, v139
	v_cvt_pk_bf16_f32 v223, v156, v157
	v_cvt_pk_bf16_f32 v227, v140, v141
	v_cvt_pk_bf16_f32 v224, v158, v159
	v_cvt_pk_bf16_f32 v228, v142, v143
	v_cvt_pk_bf16_f32 v225, v160, v161
	v_cvt_pk_bf16_f32 v229, v144, v145
	s_waitcnt lgkmcnt(6)
	v_mfma_f32_32x32x16_bf16 v[114:129], v[198:201], v[214:217], v[114:129]
	v_mfma_f32_32x32x16_bf16 v[50:65], v[198:201], v[218:221], v[50:65]
	ds_read_b64_tr_b16 v[198:199], v234 offset:28672
	ds_read_b64_tr_b16 v[200:201], v235 offset:28672
	s_waitcnt lgkmcnt(6)
	v_mfma_f32_32x32x16_bf16 v[98:113], v[202:205], v[214:217], v[98:113]
	v_mfma_f32_32x32x16_bf16 v[34:49], v[202:205], v[218:221], v[34:49]
	ds_read_b64_tr_b16 v[202:203], v237 offset:28672
	ds_read_b64_tr_b16 v[204:205], v236 offset:28672
	s_waitcnt lgkmcnt(6)
	v_mfma_f32_32x32x16_bf16 v[82:97], v[208:211], v[214:217], v[82:97]
	v_mfma_f32_32x32x16_bf16 v[18:33], v[208:211], v[218:221], v[18:33]
	ds_read_b64_tr_b16 v[208:209], v238 offset:28672
	ds_read_b64_tr_b16 v[210:211], v239 offset:28672
	s_waitcnt lgkmcnt(6)
	v_mfma_f32_32x32x16_bf16 v[66:81], v[230:233], v[214:217], v[66:81]
	v_mfma_f32_32x32x16_bf16 v[2:17], v[230:233], v[218:221], v[2:17]
	ds_read_b64_tr_b16 v[230:231], v250 offset:28672
	ds_read_b64_tr_b16 v[232:233], v251 offset:28672
	s_waitcnt lgkmcnt(6)
	v_mfma_f32_32x32x16_bf16 v[114:129], v[198:201], v[222:225], v[114:129]
	v_mfma_f32_32x32x16_bf16 v[50:65], v[198:201], v[226:229], v[50:65]
	s_waitcnt lgkmcnt(4)
	v_mfma_f32_32x32x16_bf16 v[98:113], v[202:205], v[222:225], v[98:113]
	v_mfma_f32_32x32x16_bf16 v[34:49], v[202:205], v[226:229], v[34:49]
	s_waitcnt lgkmcnt(2)
	v_mfma_f32_32x32x16_bf16 v[82:97], v[208:211], v[222:225], v[82:97]
	v_mfma_f32_32x32x16_bf16 v[18:33], v[208:211], v[226:229], v[18:33]
	s_waitcnt lgkmcnt(0)
	v_mfma_f32_32x32x16_bf16 v[66:81], v[230:233], v[222:225], v[66:81]
	v_mfma_f32_32x32x16_bf16 v[2:17], v[230:233], v[226:229], v[2:17]
	s_setprio 0
	s_branch .Lad_epi
